# EpiResid epilogues of the two bf16-residual GEMM phases rewritten: SGPR-base addressing, packed f32 squares, batched row-sum reduction and atomics
# speedup vs baseline: 1.0079x; 1.0002x over previous
.LBB0_806:
	v_lshl_add_u32 v170, s36, 8, v186
	v_lshl_or_b32 v168, s34, 8, v188
	v_lshlrev_b32_e32 v206, 2, v170
	v_lshlrev_b32_e32 v170, 11, v170
	v_lshl_add_u32 v204, v168, 1, v170
	v_mov_b32_e32 v205, v204
	global_load_dwordx4 v[128:131], v204, s[8:9]
	global_load_dwordx4 v[144:147], v204, s[8:9] offset:256
	v_add_u32_e32 v204, 0x8000, v204
	global_load_dwordx4 v[132:135], v204, s[8:9]
	global_load_dwordx4 v[148:151], v204, s[8:9] offset:256
	v_add_u32_e32 v204, 0x8000, v204
	global_load_dwordx4 v[136:139], v204, s[8:9]
	global_load_dwordx4 v[196:199], v204, s[8:9] offset:256
	v_add_u32_e32 v204, 0x8000, v204
	global_load_dwordx4 v[140:143], v204, s[8:9]
	global_load_dwordx4 v[200:203], v204, s[8:9] offset:256
	v_add_u32_e32 v204, 0x28000, v204
	v_xor_b32_e32 v194, 16, v192
	v_xor_b32_e32 v193, 32, v192
	v_lshlrev_b32_e32 v194, 2, v194
	v_lshlrev_b32_e32 v193, 2, v193
	s_waitcnt vmcnt(0)
	v_lshlrev_b32_e32 v168, 16, v128
	v_and_b32_e32 v169, 0xffff0000, v128
	v_lshlrev_b32_e32 v170, 16, v129
	v_and_b32_e32 v171, 0xffff0000, v129
	v_lshlrev_b32_e32 v172, 16, v130
	v_and_b32_e32 v173, 0xffff0000, v130
	v_lshlrev_b32_e32 v174, 16, v131
	v_and_b32_e32 v175, 0xffff0000, v131
	v_pk_add_f32 v[124:125], v[124:125], v[168:169]
	v_pk_add_f32 v[126:127], v[126:127], v[170:171]
	v_pk_add_f32 v[120:121], v[120:121], v[172:173]
	v_pk_add_f32 v[122:123], v[122:123], v[174:175]
	v_pk_mul_f32 v[176:177], v[124:125], v[124:125]
	v_pk_fma_f32 v[176:177], v[126:127], v[126:127], v[176:177]
	v_pk_fma_f32 v[176:177], v[120:121], v[120:121], v[176:177]
	v_pk_fma_f32 v[176:177], v[122:123], v[122:123], v[176:177]
	v_cvt_pk_bf16_f32 v124, v124, v125
	v_cvt_pk_bf16_f32 v125, v126, v127
	v_cvt_pk_bf16_f32 v126, v120, v121
	v_cvt_pk_bf16_f32 v127, v122, v123
	v_lshlrev_b32_e32 v168, 16, v144
	v_and_b32_e32 v169, 0xffff0000, v144
	v_lshlrev_b32_e32 v170, 16, v145
	v_and_b32_e32 v171, 0xffff0000, v145
	v_lshlrev_b32_e32 v172, 16, v146
	v_and_b32_e32 v173, 0xffff0000, v146
	v_lshlrev_b32_e32 v174, 16, v147
	v_and_b32_e32 v175, 0xffff0000, v147
	v_pk_add_f32 v[116:117], v[116:117], v[168:169]
	v_pk_add_f32 v[118:119], v[118:119], v[170:171]
	v_pk_add_f32 v[112:113], v[112:113], v[172:173]
	v_pk_add_f32 v[114:115], v[114:115], v[174:175]
	v_pk_fma_f32 v[176:177], v[116:117], v[116:117], v[176:177]
	v_pk_fma_f32 v[176:177], v[118:119], v[118:119], v[176:177]
	v_pk_fma_f32 v[176:177], v[112:113], v[112:113], v[176:177]
	v_pk_fma_f32 v[176:177], v[114:115], v[114:115], v[176:177]
	v_cvt_pk_bf16_f32 v116, v116, v117
	v_cvt_pk_bf16_f32 v117, v118, v119
	v_cvt_pk_bf16_f32 v118, v112, v113
	v_cvt_pk_bf16_f32 v119, v114, v115
	v_add_f32_e32 v178, v176, v177
	global_store_dwordx4 v205, v[124:127], s[6:7]
	global_store_dwordx4 v205, v[116:119], s[6:7] offset:256
	v_add_u32_e32 v205, 0x8000, v205
	v_lshlrev_b32_e32 v168, 16, v132
	v_and_b32_e32 v169, 0xffff0000, v132
	v_lshlrev_b32_e32 v170, 16, v133
	v_and_b32_e32 v171, 0xffff0000, v133
	v_lshlrev_b32_e32 v172, 16, v134
	v_and_b32_e32 v173, 0xffff0000, v134
	v_lshlrev_b32_e32 v174, 16, v135
	v_and_b32_e32 v175, 0xffff0000, v135
	v_pk_add_f32 v[108:109], v[108:109], v[168:169]
	v_pk_add_f32 v[110:111], v[110:111], v[170:171]
	v_pk_add_f32 v[104:105], v[104:105], v[172:173]
	v_pk_add_f32 v[106:107], v[106:107], v[174:175]
	v_pk_mul_f32 v[176:177], v[108:109], v[108:109]
	v_pk_fma_f32 v[176:177], v[110:111], v[110:111], v[176:177]
	v_pk_fma_f32 v[176:177], v[104:105], v[104:105], v[176:177]
	v_pk_fma_f32 v[176:177], v[106:107], v[106:107], v[176:177]
	v_cvt_pk_bf16_f32 v108, v108, v109
	v_cvt_pk_bf16_f32 v109, v110, v111
	v_cvt_pk_bf16_f32 v110, v104, v105
	v_cvt_pk_bf16_f32 v111, v106, v107
	v_lshlrev_b32_e32 v168, 16, v148
	v_and_b32_e32 v169, 0xffff0000, v148
	v_lshlrev_b32_e32 v170, 16, v149
	v_and_b32_e32 v171, 0xffff0000, v149
	v_lshlrev_b32_e32 v172, 16, v150
	v_and_b32_e32 v173, 0xffff0000, v150
	v_lshlrev_b32_e32 v174, 16, v151
	v_and_b32_e32 v175, 0xffff0000, v151
	v_pk_add_f32 v[100:101], v[100:101], v[168:169]
	v_pk_add_f32 v[102:103], v[102:103], v[170:171]
	v_pk_add_f32 v[96:97], v[96:97], v[172:173]
	v_pk_add_f32 v[98:99], v[98:99], v[174:175]
	v_pk_fma_f32 v[176:177], v[100:101], v[100:101], v[176:177]
	v_pk_fma_f32 v[176:177], v[102:103], v[102:103], v[176:177]
	v_pk_fma_f32 v[176:177], v[96:97], v[96:97], v[176:177]
	v_pk_fma_f32 v[176:177], v[98:99], v[98:99], v[176:177]
	v_cvt_pk_bf16_f32 v100, v100, v101
	v_cvt_pk_bf16_f32 v101, v102, v103
	v_cvt_pk_bf16_f32 v102, v96, v97
	v_cvt_pk_bf16_f32 v103, v98, v99
	v_add_f32_e32 v179, v176, v177
	global_store_dwordx4 v205, v[108:111], s[6:7]
	global_store_dwordx4 v205, v[100:103], s[6:7] offset:256
	v_add_u32_e32 v205, 0x8000, v205
	global_load_dwordx4 v[112:115], v204, s[8:9]
	global_load_dwordx4 v[116:119], v204, s[8:9] offset:256
	v_add_u32_e32 v204, 0x8000, v204
	global_load_dwordx4 v[120:123], v204, s[8:9]
	global_load_dwordx4 v[124:127], v204, s[8:9] offset:256
	v_add_u32_e32 v204, 0x8000, v204
	global_load_dwordx4 v[96:99], v204, s[8:9]
	global_load_dwordx4 v[100:103], v204, s[8:9] offset:256
	v_add_u32_e32 v204, 0x8000, v204
	global_load_dwordx4 v[104:107], v204, s[8:9]
	global_load_dwordx4 v[108:111], v204, s[8:9] offset:256
	v_lshlrev_b32_e32 v168, 16, v136
	v_and_b32_e32 v169, 0xffff0000, v136
	v_lshlrev_b32_e32 v170, 16, v137
	v_and_b32_e32 v171, 0xffff0000, v137
	v_lshlrev_b32_e32 v172, 16, v138
	v_and_b32_e32 v173, 0xffff0000, v138
	v_lshlrev_b32_e32 v174, 16, v139
	v_and_b32_e32 v175, 0xffff0000, v139
	v_pk_add_f32 v[92:93], v[92:93], v[168:169]
	v_pk_add_f32 v[94:95], v[94:95], v[170:171]
	v_pk_add_f32 v[88:89], v[88:89], v[172:173]
	v_pk_add_f32 v[90:91], v[90:91], v[174:175]
	v_pk_mul_f32 v[176:177], v[92:93], v[92:93]
	v_pk_fma_f32 v[176:177], v[94:95], v[94:95], v[176:177]
	v_pk_fma_f32 v[176:177], v[88:89], v[88:89], v[176:177]
	v_pk_fma_f32 v[176:177], v[90:91], v[90:91], v[176:177]
	v_cvt_pk_bf16_f32 v92, v92, v93
	v_cvt_pk_bf16_f32 v93, v94, v95
	v_cvt_pk_bf16_f32 v94, v88, v89
	v_cvt_pk_bf16_f32 v95, v90, v91
	v_lshlrev_b32_e32 v168, 16, v196
	v_and_b32_e32 v169, 0xffff0000, v196
	v_lshlrev_b32_e32 v170, 16, v197
	v_and_b32_e32 v171, 0xffff0000, v197
	v_lshlrev_b32_e32 v172, 16, v198
	v_and_b32_e32 v173, 0xffff0000, v198
	v_lshlrev_b32_e32 v174, 16, v199
	v_and_b32_e32 v175, 0xffff0000, v199
	v_pk_add_f32 v[84:85], v[84:85], v[168:169]
	v_pk_add_f32 v[86:87], v[86:87], v[170:171]
	v_pk_add_f32 v[80:81], v[80:81], v[172:173]
	v_pk_add_f32 v[82:83], v[82:83], v[174:175]
	v_pk_fma_f32 v[176:177], v[84:85], v[84:85], v[176:177]
	v_pk_fma_f32 v[176:177], v[86:87], v[86:87], v[176:177]
	v_pk_fma_f32 v[176:177], v[80:81], v[80:81], v[176:177]
	v_pk_fma_f32 v[176:177], v[82:83], v[82:83], v[176:177]
	v_cvt_pk_bf16_f32 v84, v84, v85
	v_cvt_pk_bf16_f32 v85, v86, v87
	v_cvt_pk_bf16_f32 v86, v80, v81
	v_cvt_pk_bf16_f32 v87, v82, v83
	v_add_f32_e32 v180, v176, v177
	global_store_dwordx4 v205, v[92:95], s[6:7]
	global_store_dwordx4 v205, v[84:87], s[6:7] offset:256
	v_add_u32_e32 v205, 0x8000, v205
	v_lshlrev_b32_e32 v168, 16, v140
	v_and_b32_e32 v169, 0xffff0000, v140
	v_lshlrev_b32_e32 v170, 16, v141
	v_and_b32_e32 v171, 0xffff0000, v141
	v_lshlrev_b32_e32 v172, 16, v142
	v_and_b32_e32 v173, 0xffff0000, v142
	v_lshlrev_b32_e32 v174, 16, v143
	v_and_b32_e32 v175, 0xffff0000, v143
	v_pk_add_f32 v[76:77], v[76:77], v[168:169]
	v_pk_add_f32 v[78:79], v[78:79], v[170:171]
	v_pk_add_f32 v[72:73], v[72:73], v[172:173]
	v_pk_add_f32 v[74:75], v[74:75], v[174:175]
	v_pk_mul_f32 v[176:177], v[76:77], v[76:77]
	v_pk_fma_f32 v[176:177], v[78:79], v[78:79], v[176:177]
	v_pk_fma_f32 v[176:177], v[72:73], v[72:73], v[176:177]
	v_pk_fma_f32 v[176:177], v[74:75], v[74:75], v[176:177]
	v_cvt_pk_bf16_f32 v76, v76, v77
	v_cvt_pk_bf16_f32 v77, v78, v79
	v_cvt_pk_bf16_f32 v78, v72, v73
	v_cvt_pk_bf16_f32 v79, v74, v75
	v_lshlrev_b32_e32 v168, 16, v200
	v_and_b32_e32 v169, 0xffff0000, v200
	v_lshlrev_b32_e32 v170, 16, v201
	v_and_b32_e32 v171, 0xffff0000, v201
	v_lshlrev_b32_e32 v172, 16, v202
	v_and_b32_e32 v173, 0xffff0000, v202
	v_lshlrev_b32_e32 v174, 16, v203
	v_and_b32_e32 v175, 0xffff0000, v203
	v_pk_add_f32 v[68:69], v[68:69], v[168:169]
	v_pk_add_f32 v[70:71], v[70:71], v[170:171]
	v_pk_add_f32 v[64:65], v[64:65], v[172:173]
	v_pk_add_f32 v[66:67], v[66:67], v[174:175]
	v_pk_fma_f32 v[176:177], v[68:69], v[68:69], v[176:177]
	v_pk_fma_f32 v[176:177], v[70:71], v[70:71], v[176:177]
	v_pk_fma_f32 v[176:177], v[64:65], v[64:65], v[176:177]
	v_pk_fma_f32 v[176:177], v[66:67], v[66:67], v[176:177]
	v_cvt_pk_bf16_f32 v68, v68, v69
	v_cvt_pk_bf16_f32 v69, v70, v71
	v_cvt_pk_bf16_f32 v70, v64, v65
	v_cvt_pk_bf16_f32 v71, v66, v67
	v_add_f32_e32 v181, v176, v177
	global_store_dwordx4 v205, v[76:79], s[6:7]
	global_store_dwordx4 v205, v[68:71], s[6:7] offset:256
	v_add_u32_e32 v205, 0x28000, v205
	s_waitcnt vmcnt(4)
	v_lshlrev_b32_e32 v168, 16, v112
	v_and_b32_e32 v169, 0xffff0000, v112
	v_lshlrev_b32_e32 v170, 16, v113
	v_and_b32_e32 v171, 0xffff0000, v113
	v_lshlrev_b32_e32 v172, 16, v114
	v_and_b32_e32 v173, 0xffff0000, v114
	v_lshlrev_b32_e32 v174, 16, v115
	v_and_b32_e32 v175, 0xffff0000, v115
	v_pk_add_f32 v[60:61], v[60:61], v[168:169]
	v_pk_add_f32 v[62:63], v[62:63], v[170:171]
	v_pk_add_f32 v[56:57], v[56:57], v[172:173]
	v_pk_add_f32 v[58:59], v[58:59], v[174:175]
	v_pk_mul_f32 v[176:177], v[60:61], v[60:61]
	v_pk_fma_f32 v[176:177], v[62:63], v[62:63], v[176:177]
	v_pk_fma_f32 v[176:177], v[56:57], v[56:57], v[176:177]
	v_pk_fma_f32 v[176:177], v[58:59], v[58:59], v[176:177]
	v_cvt_pk_bf16_f32 v60, v60, v61
	v_cvt_pk_bf16_f32 v61, v62, v63
	v_cvt_pk_bf16_f32 v62, v56, v57
	v_cvt_pk_bf16_f32 v63, v58, v59
	v_lshlrev_b32_e32 v168, 16, v116
	v_and_b32_e32 v169, 0xffff0000, v116
	v_lshlrev_b32_e32 v170, 16, v117
	v_and_b32_e32 v171, 0xffff0000, v117
	v_lshlrev_b32_e32 v172, 16, v118
	v_and_b32_e32 v173, 0xffff0000, v118
	v_lshlrev_b32_e32 v174, 16, v119
	v_and_b32_e32 v175, 0xffff0000, v119
	v_pk_add_f32 v[52:53], v[52:53], v[168:169]
	v_pk_add_f32 v[54:55], v[54:55], v[170:171]
	v_pk_add_f32 v[48:49], v[48:49], v[172:173]
	v_pk_add_f32 v[50:51], v[50:51], v[174:175]
	v_pk_fma_f32 v[176:177], v[52:53], v[52:53], v[176:177]
	v_pk_fma_f32 v[176:177], v[54:55], v[54:55], v[176:177]
	v_pk_fma_f32 v[176:177], v[48:49], v[48:49], v[176:177]
	v_pk_fma_f32 v[176:177], v[50:51], v[50:51], v[176:177]
	v_cvt_pk_bf16_f32 v52, v52, v53
	v_cvt_pk_bf16_f32 v53, v54, v55
	v_cvt_pk_bf16_f32 v54, v48, v49
	v_cvt_pk_bf16_f32 v55, v50, v51
	v_add_f32_e32 v182, v176, v177
	global_store_dwordx4 v205, v[60:63], s[6:7]
	global_store_dwordx4 v205, v[52:55], s[6:7] offset:256
	v_add_u32_e32 v205, 0x8000, v205
	v_lshlrev_b32_e32 v168, 16, v120
	v_and_b32_e32 v169, 0xffff0000, v120
	v_lshlrev_b32_e32 v170, 16, v121
	v_and_b32_e32 v171, 0xffff0000, v121
	v_lshlrev_b32_e32 v172, 16, v122
	v_and_b32_e32 v173, 0xffff0000, v122
	v_lshlrev_b32_e32 v174, 16, v123
	v_and_b32_e32 v175, 0xffff0000, v123
	v_pk_add_f32 v[44:45], v[44:45], v[168:169]
	v_pk_add_f32 v[46:47], v[46:47], v[170:171]
	v_pk_add_f32 v[40:41], v[40:41], v[172:173]
	v_pk_add_f32 v[42:43], v[42:43], v[174:175]
	v_pk_mul_f32 v[176:177], v[44:45], v[44:45]
	v_pk_fma_f32 v[176:177], v[46:47], v[46:47], v[176:177]
	v_pk_fma_f32 v[176:177], v[40:41], v[40:41], v[176:177]
	v_pk_fma_f32 v[176:177], v[42:43], v[42:43], v[176:177]
	v_cvt_pk_bf16_f32 v44, v44, v45
	v_cvt_pk_bf16_f32 v45, v46, v47
	v_cvt_pk_bf16_f32 v46, v40, v41
	v_cvt_pk_bf16_f32 v47, v42, v43
	v_lshlrev_b32_e32 v168, 16, v124
	v_and_b32_e32 v169, 0xffff0000, v124
	v_lshlrev_b32_e32 v170, 16, v125
	v_and_b32_e32 v171, 0xffff0000, v125
	v_lshlrev_b32_e32 v172, 16, v126
	v_and_b32_e32 v173, 0xffff0000, v126
	v_lshlrev_b32_e32 v174, 16, v127
	v_and_b32_e32 v175, 0xffff0000, v127
	v_pk_add_f32 v[36:37], v[36:37], v[168:169]
	v_pk_add_f32 v[38:39], v[38:39], v[170:171]
	v_pk_add_f32 v[32:33], v[32:33], v[172:173]
	v_pk_add_f32 v[34:35], v[34:35], v[174:175]
	v_pk_fma_f32 v[176:177], v[36:37], v[36:37], v[176:177]
	v_pk_fma_f32 v[176:177], v[38:39], v[38:39], v[176:177]
	v_pk_fma_f32 v[176:177], v[32:33], v[32:33], v[176:177]
	v_pk_fma_f32 v[176:177], v[34:35], v[34:35], v[176:177]
	v_cvt_pk_bf16_f32 v36, v36, v37
	v_cvt_pk_bf16_f32 v37, v38, v39
	v_cvt_pk_bf16_f32 v38, v32, v33
	v_cvt_pk_bf16_f32 v39, v34, v35
	v_add_f32_e32 v183, v176, v177
	global_store_dwordx4 v205, v[44:47], s[6:7]
	global_store_dwordx4 v205, v[36:39], s[6:7] offset:256
	v_add_u32_e32 v205, 0x8000, v205
	v_lshlrev_b32_e32 v168, 16, v96
	v_and_b32_e32 v169, 0xffff0000, v96
	v_lshlrev_b32_e32 v170, 16, v97
	v_and_b32_e32 v171, 0xffff0000, v97
	v_lshlrev_b32_e32 v172, 16, v98
	v_and_b32_e32 v173, 0xffff0000, v98
	v_lshlrev_b32_e32 v174, 16, v99
	v_and_b32_e32 v175, 0xffff0000, v99
	v_pk_add_f32 v[28:29], v[28:29], v[168:169]
	v_pk_add_f32 v[30:31], v[30:31], v[170:171]
	v_pk_add_f32 v[24:25], v[24:25], v[172:173]
	v_pk_add_f32 v[26:27], v[26:27], v[174:175]
	v_pk_mul_f32 v[176:177], v[28:29], v[28:29]
	v_pk_fma_f32 v[176:177], v[30:31], v[30:31], v[176:177]
	v_pk_fma_f32 v[176:177], v[24:25], v[24:25], v[176:177]
	v_pk_fma_f32 v[176:177], v[26:27], v[26:27], v[176:177]
	v_cvt_pk_bf16_f32 v28, v28, v29
	v_cvt_pk_bf16_f32 v29, v30, v31
	v_cvt_pk_bf16_f32 v30, v24, v25
	v_cvt_pk_bf16_f32 v31, v26, v27
	v_lshlrev_b32_e32 v168, 16, v100
	v_and_b32_e32 v169, 0xffff0000, v100
	v_lshlrev_b32_e32 v170, 16, v101
	v_and_b32_e32 v171, 0xffff0000, v101
	v_lshlrev_b32_e32 v172, 16, v102
	v_and_b32_e32 v173, 0xffff0000, v102
	v_lshlrev_b32_e32 v174, 16, v103
	v_and_b32_e32 v175, 0xffff0000, v103
	v_pk_add_f32 v[20:21], v[20:21], v[168:169]
	v_pk_add_f32 v[22:23], v[22:23], v[170:171]
	v_pk_add_f32 v[16:17], v[16:17], v[172:173]
	v_pk_add_f32 v[18:19], v[18:19], v[174:175]
	v_pk_fma_f32 v[176:177], v[20:21], v[20:21], v[176:177]
	v_pk_fma_f32 v[176:177], v[22:23], v[22:23], v[176:177]
	v_pk_fma_f32 v[176:177], v[16:17], v[16:17], v[176:177]
	v_pk_fma_f32 v[176:177], v[18:19], v[18:19], v[176:177]
	v_cvt_pk_bf16_f32 v20, v20, v21
	v_cvt_pk_bf16_f32 v21, v22, v23
	v_cvt_pk_bf16_f32 v22, v16, v17
	v_cvt_pk_bf16_f32 v23, v18, v19
	v_add_f32_e32 v184, v176, v177
	global_store_dwordx4 v205, v[28:31], s[6:7]
	global_store_dwordx4 v205, v[20:23], s[6:7] offset:256
	v_add_u32_e32 v205, 0x8000, v205
	v_lshlrev_b32_e32 v168, 16, v104
	v_and_b32_e32 v169, 0xffff0000, v104
	v_lshlrev_b32_e32 v170, 16, v105
	v_and_b32_e32 v171, 0xffff0000, v105
	v_lshlrev_b32_e32 v172, 16, v106
	v_and_b32_e32 v173, 0xffff0000, v106
	v_lshlrev_b32_e32 v174, 16, v107
	v_and_b32_e32 v175, 0xffff0000, v107
	v_pk_add_f32 v[12:13], v[12:13], v[168:169]
	v_pk_add_f32 v[14:15], v[14:15], v[170:171]
	v_pk_add_f32 v[8:9], v[8:9], v[172:173]
	v_pk_add_f32 v[10:11], v[10:11], v[174:175]
	v_pk_mul_f32 v[176:177], v[12:13], v[12:13]
	v_pk_fma_f32 v[176:177], v[14:15], v[14:15], v[176:177]
	v_pk_fma_f32 v[176:177], v[8:9], v[8:9], v[176:177]
	v_pk_fma_f32 v[176:177], v[10:11], v[10:11], v[176:177]
	v_cvt_pk_bf16_f32 v12, v12, v13
	v_cvt_pk_bf16_f32 v13, v14, v15
	v_cvt_pk_bf16_f32 v14, v8, v9
	v_cvt_pk_bf16_f32 v15, v10, v11
	v_lshlrev_b32_e32 v168, 16, v108
	v_and_b32_e32 v169, 0xffff0000, v108
	v_lshlrev_b32_e32 v170, 16, v109
	v_and_b32_e32 v171, 0xffff0000, v109
	v_lshlrev_b32_e32 v172, 16, v110
	v_and_b32_e32 v173, 0xffff0000, v110
	v_lshlrev_b32_e32 v174, 16, v111
	v_and_b32_e32 v175, 0xffff0000, v111
	v_pk_add_f32 v[4:5], v[4:5], v[168:169]
	v_pk_add_f32 v[6:7], v[6:7], v[170:171]
	v_pk_add_f32 v[0:1], v[0:1], v[172:173]
	v_pk_add_f32 v[2:3], v[2:3], v[174:175]
	v_pk_fma_f32 v[176:177], v[4:5], v[4:5], v[176:177]
	v_pk_fma_f32 v[176:177], v[6:7], v[6:7], v[176:177]
	v_pk_fma_f32 v[176:177], v[0:1], v[0:1], v[176:177]
	v_pk_fma_f32 v[176:177], v[2:3], v[2:3], v[176:177]
	v_cvt_pk_bf16_f32 v4, v4, v5
	v_cvt_pk_bf16_f32 v5, v6, v7
	v_cvt_pk_bf16_f32 v6, v0, v1
	v_cvt_pk_bf16_f32 v7, v2, v3
	v_add_f32_e32 v185, v176, v177
	global_store_dwordx4 v205, v[12:15], s[6:7]
	global_store_dwordx4 v205, v[4:7], s[6:7] offset:256
	ds_bpermute_b32 v168, v194, v178
	ds_bpermute_b32 v169, v194, v179
	ds_bpermute_b32 v170, v194, v180
	ds_bpermute_b32 v171, v194, v181
	ds_bpermute_b32 v172, v194, v182
	ds_bpermute_b32 v173, v194, v183
	ds_bpermute_b32 v174, v194, v184
	ds_bpermute_b32 v175, v194, v185
	s_waitcnt lgkmcnt(0)
	v_add_f32_e32 v178, v178, v168
	v_add_f32_e32 v179, v179, v169
	v_add_f32_e32 v180, v180, v170
	v_add_f32_e32 v181, v181, v171
	v_add_f32_e32 v182, v182, v172
	v_add_f32_e32 v183, v183, v173
	v_add_f32_e32 v184, v184, v174
	v_add_f32_e32 v185, v185, v175
	ds_bpermute_b32 v168, v193, v178
	ds_bpermute_b32 v169, v193, v179
	ds_bpermute_b32 v170, v193, v180
	ds_bpermute_b32 v171, v193, v181
	ds_bpermute_b32 v172, v193, v182
	ds_bpermute_b32 v173, v193, v183
	ds_bpermute_b32 v174, v193, v184
	ds_bpermute_b32 v175, v193, v185
	s_waitcnt lgkmcnt(0)
	v_add_f32_e32 v178, v178, v168
	v_add_f32_e32 v179, v179, v169
	v_add_f32_e32 v180, v180, v170
	v_add_f32_e32 v181, v181, v171
	v_add_f32_e32 v182, v182, v172
	v_add_f32_e32 v183, v183, v173
	v_add_f32_e32 v184, v184, v174
	v_add_f32_e32 v185, v185, v175
	s_and_saveexec_b64 s[0:1], s[2:3]
	global_atomic_add_f32 v206, v178, s[18:19]
	global_atomic_add_f32 v206, v179, s[18:19] offset:64
	global_atomic_add_f32 v206, v180, s[18:19] offset:128
	global_atomic_add_f32 v206, v181, s[18:19] offset:192
	global_atomic_add_f32 v206, v182, s[18:19] offset:512
	global_atomic_add_f32 v206, v183, s[18:19] offset:576
	global_atomic_add_f32 v206, v184, s[18:19] offset:640
	global_atomic_add_f32 v206, v185, s[18:19] offset:704
	s_or_b64 exec, exec, s[0:1]
	s_and_b64 vcc, exec, s[4:5]
	s_mov_b64 s[0:1], -1
	s_cbranch_vccnz .LBB0_793
	s_andn2_b64 vcc, exec, s[16:17]
	s_cbranch_vccnz .LBB0_792
	s_barrier
	s_branch .LBB0_792

.LBB0_978:
	v_lshl_add_u32 v170, s53, 8, v186
	v_lshl_or_b32 v168, s52, 8, v188
	v_lshlrev_b32_e32 v206, 2, v170
	v_lshlrev_b32_e32 v170, 11, v170
	v_lshl_add_u32 v204, v168, 1, v170
	v_mov_b32_e32 v205, v204
	global_load_dwordx4 v[128:131], v204, s[6:7]
	global_load_dwordx4 v[144:147], v204, s[6:7] offset:256
	v_add_u32_e32 v204, 0x8000, v204
	global_load_dwordx4 v[132:135], v204, s[6:7]
	global_load_dwordx4 v[148:151], v204, s[6:7] offset:256
	v_add_u32_e32 v204, 0x8000, v204
	global_load_dwordx4 v[136:139], v204, s[6:7]
	global_load_dwordx4 v[196:199], v204, s[6:7] offset:256
	v_add_u32_e32 v204, 0x8000, v204
	global_load_dwordx4 v[140:143], v204, s[6:7]
	global_load_dwordx4 v[200:203], v204, s[6:7] offset:256
	v_add_u32_e32 v204, 0x28000, v204
	v_xor_b32_e32 v194, 16, v192
	v_xor_b32_e32 v193, 32, v192
	v_lshlrev_b32_e32 v194, 2, v194
	v_lshlrev_b32_e32 v193, 2, v193
	s_waitcnt vmcnt(0)
	v_lshlrev_b32_e32 v168, 16, v128
	v_and_b32_e32 v169, 0xffff0000, v128
	v_lshlrev_b32_e32 v170, 16, v129
	v_and_b32_e32 v171, 0xffff0000, v129
	v_lshlrev_b32_e32 v172, 16, v130
	v_and_b32_e32 v173, 0xffff0000, v130
	v_lshlrev_b32_e32 v174, 16, v131
	v_and_b32_e32 v175, 0xffff0000, v131
	v_pk_add_f32 v[124:125], v[124:125], v[168:169]
	v_pk_add_f32 v[126:127], v[126:127], v[170:171]
	v_pk_add_f32 v[120:121], v[120:121], v[172:173]
	v_pk_add_f32 v[122:123], v[122:123], v[174:175]
	v_pk_mul_f32 v[176:177], v[124:125], v[124:125]
	v_pk_fma_f32 v[176:177], v[126:127], v[126:127], v[176:177]
	v_pk_fma_f32 v[176:177], v[120:121], v[120:121], v[176:177]
	v_pk_fma_f32 v[176:177], v[122:123], v[122:123], v[176:177]
	v_cvt_pk_bf16_f32 v124, v124, v125
	v_cvt_pk_bf16_f32 v125, v126, v127
	v_cvt_pk_bf16_f32 v126, v120, v121
	v_cvt_pk_bf16_f32 v127, v122, v123
	v_lshlrev_b32_e32 v168, 16, v144
	v_and_b32_e32 v169, 0xffff0000, v144
	v_lshlrev_b32_e32 v170, 16, v145
	v_and_b32_e32 v171, 0xffff0000, v145
	v_lshlrev_b32_e32 v172, 16, v146
	v_and_b32_e32 v173, 0xffff0000, v146
	v_lshlrev_b32_e32 v174, 16, v147
	v_and_b32_e32 v175, 0xffff0000, v147
	v_pk_add_f32 v[116:117], v[116:117], v[168:169]
	v_pk_add_f32 v[118:119], v[118:119], v[170:171]
	v_pk_add_f32 v[112:113], v[112:113], v[172:173]
	v_pk_add_f32 v[114:115], v[114:115], v[174:175]
	v_pk_fma_f32 v[176:177], v[116:117], v[116:117], v[176:177]
	v_pk_fma_f32 v[176:177], v[118:119], v[118:119], v[176:177]
	v_pk_fma_f32 v[176:177], v[112:113], v[112:113], v[176:177]
	v_pk_fma_f32 v[176:177], v[114:115], v[114:115], v[176:177]
	v_cvt_pk_bf16_f32 v116, v116, v117
	v_cvt_pk_bf16_f32 v117, v118, v119
	v_cvt_pk_bf16_f32 v118, v112, v113
	v_cvt_pk_bf16_f32 v119, v114, v115
	v_add_f32_e32 v178, v176, v177
	global_store_dwordx4 v205, v[124:127], s[8:9]
	global_store_dwordx4 v205, v[116:119], s[8:9] offset:256
	v_add_u32_e32 v205, 0x8000, v205
	v_lshlrev_b32_e32 v168, 16, v132
	v_and_b32_e32 v169, 0xffff0000, v132
	v_lshlrev_b32_e32 v170, 16, v133
	v_and_b32_e32 v171, 0xffff0000, v133
	v_lshlrev_b32_e32 v172, 16, v134
	v_and_b32_e32 v173, 0xffff0000, v134
	v_lshlrev_b32_e32 v174, 16, v135
	v_and_b32_e32 v175, 0xffff0000, v135
	v_pk_add_f32 v[108:109], v[108:109], v[168:169]
	v_pk_add_f32 v[110:111], v[110:111], v[170:171]
	v_pk_add_f32 v[104:105], v[104:105], v[172:173]
	v_pk_add_f32 v[106:107], v[106:107], v[174:175]
	v_pk_mul_f32 v[176:177], v[108:109], v[108:109]
	v_pk_fma_f32 v[176:177], v[110:111], v[110:111], v[176:177]
	v_pk_fma_f32 v[176:177], v[104:105], v[104:105], v[176:177]
	v_pk_fma_f32 v[176:177], v[106:107], v[106:107], v[176:177]
	v_cvt_pk_bf16_f32 v108, v108, v109
	v_cvt_pk_bf16_f32 v109, v110, v111
	v_cvt_pk_bf16_f32 v110, v104, v105
	v_cvt_pk_bf16_f32 v111, v106, v107
	v_lshlrev_b32_e32 v168, 16, v148
	v_and_b32_e32 v169, 0xffff0000, v148
	v_lshlrev_b32_e32 v170, 16, v149
	v_and_b32_e32 v171, 0xffff0000, v149
	v_lshlrev_b32_e32 v172, 16, v150
	v_and_b32_e32 v173, 0xffff0000, v150
	v_lshlrev_b32_e32 v174, 16, v151
	v_and_b32_e32 v175, 0xffff0000, v151
	v_pk_add_f32 v[100:101], v[100:101], v[168:169]
	v_pk_add_f32 v[102:103], v[102:103], v[170:171]
	v_pk_add_f32 v[96:97], v[96:97], v[172:173]
	v_pk_add_f32 v[98:99], v[98:99], v[174:175]
	v_pk_fma_f32 v[176:177], v[100:101], v[100:101], v[176:177]
	v_pk_fma_f32 v[176:177], v[102:103], v[102:103], v[176:177]
	v_pk_fma_f32 v[176:177], v[96:97], v[96:97], v[176:177]
	v_pk_fma_f32 v[176:177], v[98:99], v[98:99], v[176:177]
	v_cvt_pk_bf16_f32 v100, v100, v101
	v_cvt_pk_bf16_f32 v101, v102, v103
	v_cvt_pk_bf16_f32 v102, v96, v97
	v_cvt_pk_bf16_f32 v103, v98, v99
	v_add_f32_e32 v179, v176, v177
	global_store_dwordx4 v205, v[108:111], s[8:9]
	global_store_dwordx4 v205, v[100:103], s[8:9] offset:256
	v_add_u32_e32 v205, 0x8000, v205
	global_load_dwordx4 v[112:115], v204, s[6:7]
	global_load_dwordx4 v[116:119], v204, s[6:7] offset:256
	v_add_u32_e32 v204, 0x8000, v204
	global_load_dwordx4 v[120:123], v204, s[6:7]
	global_load_dwordx4 v[124:127], v204, s[6:7] offset:256
	v_add_u32_e32 v204, 0x8000, v204
	global_load_dwordx4 v[96:99], v204, s[6:7]
	global_load_dwordx4 v[100:103], v204, s[6:7] offset:256
	v_add_u32_e32 v204, 0x8000, v204
	global_load_dwordx4 v[104:107], v204, s[6:7]
	global_load_dwordx4 v[108:111], v204, s[6:7] offset:256
	v_lshlrev_b32_e32 v168, 16, v136
	v_and_b32_e32 v169, 0xffff0000, v136
	v_lshlrev_b32_e32 v170, 16, v137
	v_and_b32_e32 v171, 0xffff0000, v137
	v_lshlrev_b32_e32 v172, 16, v138
	v_and_b32_e32 v173, 0xffff0000, v138
	v_lshlrev_b32_e32 v174, 16, v139
	v_and_b32_e32 v175, 0xffff0000, v139
	v_pk_add_f32 v[92:93], v[92:93], v[168:169]
	v_pk_add_f32 v[94:95], v[94:95], v[170:171]
	v_pk_add_f32 v[88:89], v[88:89], v[172:173]
	v_pk_add_f32 v[90:91], v[90:91], v[174:175]
	v_pk_mul_f32 v[176:177], v[92:93], v[92:93]
	v_pk_fma_f32 v[176:177], v[94:95], v[94:95], v[176:177]
	v_pk_fma_f32 v[176:177], v[88:89], v[88:89], v[176:177]
	v_pk_fma_f32 v[176:177], v[90:91], v[90:91], v[176:177]
	v_cvt_pk_bf16_f32 v92, v92, v93
	v_cvt_pk_bf16_f32 v93, v94, v95
	v_cvt_pk_bf16_f32 v94, v88, v89
	v_cvt_pk_bf16_f32 v95, v90, v91
	v_lshlrev_b32_e32 v168, 16, v196
	v_and_b32_e32 v169, 0xffff0000, v196
	v_lshlrev_b32_e32 v170, 16, v197
	v_and_b32_e32 v171, 0xffff0000, v197
	v_lshlrev_b32_e32 v172, 16, v198
	v_and_b32_e32 v173, 0xffff0000, v198
	v_lshlrev_b32_e32 v174, 16, v199
	v_and_b32_e32 v175, 0xffff0000, v199
	v_pk_add_f32 v[84:85], v[84:85], v[168:169]
	v_pk_add_f32 v[86:87], v[86:87], v[170:171]
	v_pk_add_f32 v[80:81], v[80:81], v[172:173]
	v_pk_add_f32 v[82:83], v[82:83], v[174:175]
	v_pk_fma_f32 v[176:177], v[84:85], v[84:85], v[176:177]
	v_pk_fma_f32 v[176:177], v[86:87], v[86:87], v[176:177]
	v_pk_fma_f32 v[176:177], v[80:81], v[80:81], v[176:177]
	v_pk_fma_f32 v[176:177], v[82:83], v[82:83], v[176:177]
	v_cvt_pk_bf16_f32 v84, v84, v85
	v_cvt_pk_bf16_f32 v85, v86, v87
	v_cvt_pk_bf16_f32 v86, v80, v81
	v_cvt_pk_bf16_f32 v87, v82, v83
	v_add_f32_e32 v180, v176, v177
	global_store_dwordx4 v205, v[92:95], s[8:9]
	global_store_dwordx4 v205, v[84:87], s[8:9] offset:256
	v_add_u32_e32 v205, 0x8000, v205
	v_lshlrev_b32_e32 v168, 16, v140
	v_and_b32_e32 v169, 0xffff0000, v140
	v_lshlrev_b32_e32 v170, 16, v141
	v_and_b32_e32 v171, 0xffff0000, v141
	v_lshlrev_b32_e32 v172, 16, v142
	v_and_b32_e32 v173, 0xffff0000, v142
	v_lshlrev_b32_e32 v174, 16, v143
	v_and_b32_e32 v175, 0xffff0000, v143
	v_pk_add_f32 v[76:77], v[76:77], v[168:169]
	v_pk_add_f32 v[78:79], v[78:79], v[170:171]
	v_pk_add_f32 v[72:73], v[72:73], v[172:173]
	v_pk_add_f32 v[74:75], v[74:75], v[174:175]
	v_pk_mul_f32 v[176:177], v[76:77], v[76:77]
	v_pk_fma_f32 v[176:177], v[78:79], v[78:79], v[176:177]
	v_pk_fma_f32 v[176:177], v[72:73], v[72:73], v[176:177]
	v_pk_fma_f32 v[176:177], v[74:75], v[74:75], v[176:177]
	v_cvt_pk_bf16_f32 v76, v76, v77
	v_cvt_pk_bf16_f32 v77, v78, v79
	v_cvt_pk_bf16_f32 v78, v72, v73
	v_cvt_pk_bf16_f32 v79, v74, v75
	v_lshlrev_b32_e32 v168, 16, v200
	v_and_b32_e32 v169, 0xffff0000, v200
	v_lshlrev_b32_e32 v170, 16, v201
	v_and_b32_e32 v171, 0xffff0000, v201
	v_lshlrev_b32_e32 v172, 16, v202
	v_and_b32_e32 v173, 0xffff0000, v202
	v_lshlrev_b32_e32 v174, 16, v203
	v_and_b32_e32 v175, 0xffff0000, v203
	v_pk_add_f32 v[68:69], v[68:69], v[168:169]
	v_pk_add_f32 v[70:71], v[70:71], v[170:171]
	v_pk_add_f32 v[64:65], v[64:65], v[172:173]
	v_pk_add_f32 v[66:67], v[66:67], v[174:175]
	v_pk_fma_f32 v[176:177], v[68:69], v[68:69], v[176:177]
	v_pk_fma_f32 v[176:177], v[70:71], v[70:71], v[176:177]
	v_pk_fma_f32 v[176:177], v[64:65], v[64:65], v[176:177]
	v_pk_fma_f32 v[176:177], v[66:67], v[66:67], v[176:177]
	v_cvt_pk_bf16_f32 v68, v68, v69
	v_cvt_pk_bf16_f32 v69, v70, v71
	v_cvt_pk_bf16_f32 v70, v64, v65
	v_cvt_pk_bf16_f32 v71, v66, v67
	v_add_f32_e32 v181, v176, v177
	global_store_dwordx4 v205, v[76:79], s[8:9]
	global_store_dwordx4 v205, v[68:71], s[8:9] offset:256
	v_add_u32_e32 v205, 0x28000, v205
	s_waitcnt vmcnt(4)
	v_lshlrev_b32_e32 v168, 16, v112
	v_and_b32_e32 v169, 0xffff0000, v112
	v_lshlrev_b32_e32 v170, 16, v113
	v_and_b32_e32 v171, 0xffff0000, v113
	v_lshlrev_b32_e32 v172, 16, v114
	v_and_b32_e32 v173, 0xffff0000, v114
	v_lshlrev_b32_e32 v174, 16, v115
	v_and_b32_e32 v175, 0xffff0000, v115
	v_pk_add_f32 v[60:61], v[60:61], v[168:169]
	v_pk_add_f32 v[62:63], v[62:63], v[170:171]
	v_pk_add_f32 v[56:57], v[56:57], v[172:173]
	v_pk_add_f32 v[58:59], v[58:59], v[174:175]
	v_pk_mul_f32 v[176:177], v[60:61], v[60:61]
	v_pk_fma_f32 v[176:177], v[62:63], v[62:63], v[176:177]
	v_pk_fma_f32 v[176:177], v[56:57], v[56:57], v[176:177]
	v_pk_fma_f32 v[176:177], v[58:59], v[58:59], v[176:177]
	v_cvt_pk_bf16_f32 v60, v60, v61
	v_cvt_pk_bf16_f32 v61, v62, v63
	v_cvt_pk_bf16_f32 v62, v56, v57
	v_cvt_pk_bf16_f32 v63, v58, v59
	v_lshlrev_b32_e32 v168, 16, v116
	v_and_b32_e32 v169, 0xffff0000, v116
	v_lshlrev_b32_e32 v170, 16, v117
	v_and_b32_e32 v171, 0xffff0000, v117
	v_lshlrev_b32_e32 v172, 16, v118
	v_and_b32_e32 v173, 0xffff0000, v118
	v_lshlrev_b32_e32 v174, 16, v119
	v_and_b32_e32 v175, 0xffff0000, v119
	v_pk_add_f32 v[52:53], v[52:53], v[168:169]
	v_pk_add_f32 v[54:55], v[54:55], v[170:171]
	v_pk_add_f32 v[48:49], v[48:49], v[172:173]
	v_pk_add_f32 v[50:51], v[50:51], v[174:175]
	v_pk_fma_f32 v[176:177], v[52:53], v[52:53], v[176:177]
	v_pk_fma_f32 v[176:177], v[54:55], v[54:55], v[176:177]
	v_pk_fma_f32 v[176:177], v[48:49], v[48:49], v[176:177]
	v_pk_fma_f32 v[176:177], v[50:51], v[50:51], v[176:177]
	v_cvt_pk_bf16_f32 v52, v52, v53
	v_cvt_pk_bf16_f32 v53, v54, v55
	v_cvt_pk_bf16_f32 v54, v48, v49
	v_cvt_pk_bf16_f32 v55, v50, v51
	v_add_f32_e32 v182, v176, v177
	global_store_dwordx4 v205, v[60:63], s[8:9]
	global_store_dwordx4 v205, v[52:55], s[8:9] offset:256
	v_add_u32_e32 v205, 0x8000, v205
	v_lshlrev_b32_e32 v168, 16, v120
	v_and_b32_e32 v169, 0xffff0000, v120
	v_lshlrev_b32_e32 v170, 16, v121
	v_and_b32_e32 v171, 0xffff0000, v121
	v_lshlrev_b32_e32 v172, 16, v122
	v_and_b32_e32 v173, 0xffff0000, v122
	v_lshlrev_b32_e32 v174, 16, v123
	v_and_b32_e32 v175, 0xffff0000, v123
	v_pk_add_f32 v[44:45], v[44:45], v[168:169]
	v_pk_add_f32 v[46:47], v[46:47], v[170:171]
	v_pk_add_f32 v[40:41], v[40:41], v[172:173]
	v_pk_add_f32 v[42:43], v[42:43], v[174:175]
	v_pk_mul_f32 v[176:177], v[44:45], v[44:45]
	v_pk_fma_f32 v[176:177], v[46:47], v[46:47], v[176:177]
	v_pk_fma_f32 v[176:177], v[40:41], v[40:41], v[176:177]
	v_pk_fma_f32 v[176:177], v[42:43], v[42:43], v[176:177]
	v_cvt_pk_bf16_f32 v44, v44, v45
	v_cvt_pk_bf16_f32 v45, v46, v47
	v_cvt_pk_bf16_f32 v46, v40, v41
	v_cvt_pk_bf16_f32 v47, v42, v43
	v_lshlrev_b32_e32 v168, 16, v124
	v_and_b32_e32 v169, 0xffff0000, v124
	v_lshlrev_b32_e32 v170, 16, v125
	v_and_b32_e32 v171, 0xffff0000, v125
	v_lshlrev_b32_e32 v172, 16, v126
	v_and_b32_e32 v173, 0xffff0000, v126
	v_lshlrev_b32_e32 v174, 16, v127
	v_and_b32_e32 v175, 0xffff0000, v127
	v_pk_add_f32 v[36:37], v[36:37], v[168:169]
	v_pk_add_f32 v[38:39], v[38:39], v[170:171]
	v_pk_add_f32 v[32:33], v[32:33], v[172:173]
	v_pk_add_f32 v[34:35], v[34:35], v[174:175]
	v_pk_fma_f32 v[176:177], v[36:37], v[36:37], v[176:177]
	v_pk_fma_f32 v[176:177], v[38:39], v[38:39], v[176:177]
	v_pk_fma_f32 v[176:177], v[32:33], v[32:33], v[176:177]
	v_pk_fma_f32 v[176:177], v[34:35], v[34:35], v[176:177]
	v_cvt_pk_bf16_f32 v36, v36, v37
	v_cvt_pk_bf16_f32 v37, v38, v39
	v_cvt_pk_bf16_f32 v38, v32, v33
	v_cvt_pk_bf16_f32 v39, v34, v35
	v_add_f32_e32 v183, v176, v177
	global_store_dwordx4 v205, v[44:47], s[8:9]
	global_store_dwordx4 v205, v[36:39], s[8:9] offset:256
	v_add_u32_e32 v205, 0x8000, v205
	v_lshlrev_b32_e32 v168, 16, v96
	v_and_b32_e32 v169, 0xffff0000, v96
	v_lshlrev_b32_e32 v170, 16, v97
	v_and_b32_e32 v171, 0xffff0000, v97
	v_lshlrev_b32_e32 v172, 16, v98
	v_and_b32_e32 v173, 0xffff0000, v98
	v_lshlrev_b32_e32 v174, 16, v99
	v_and_b32_e32 v175, 0xffff0000, v99
	v_pk_add_f32 v[28:29], v[28:29], v[168:169]
	v_pk_add_f32 v[30:31], v[30:31], v[170:171]
	v_pk_add_f32 v[24:25], v[24:25], v[172:173]
	v_pk_add_f32 v[26:27], v[26:27], v[174:175]
	v_pk_mul_f32 v[176:177], v[28:29], v[28:29]
	v_pk_fma_f32 v[176:177], v[30:31], v[30:31], v[176:177]
	v_pk_fma_f32 v[176:177], v[24:25], v[24:25], v[176:177]
	v_pk_fma_f32 v[176:177], v[26:27], v[26:27], v[176:177]
	v_cvt_pk_bf16_f32 v28, v28, v29
	v_cvt_pk_bf16_f32 v29, v30, v31
	v_cvt_pk_bf16_f32 v30, v24, v25
	v_cvt_pk_bf16_f32 v31, v26, v27
	v_lshlrev_b32_e32 v168, 16, v100
	v_and_b32_e32 v169, 0xffff0000, v100
	v_lshlrev_b32_e32 v170, 16, v101
	v_and_b32_e32 v171, 0xffff0000, v101
	v_lshlrev_b32_e32 v172, 16, v102
	v_and_b32_e32 v173, 0xffff0000, v102
	v_lshlrev_b32_e32 v174, 16, v103
	v_and_b32_e32 v175, 0xffff0000, v103
	v_pk_add_f32 v[20:21], v[20:21], v[168:169]
	v_pk_add_f32 v[22:23], v[22:23], v[170:171]
	v_pk_add_f32 v[16:17], v[16:17], v[172:173]
	v_pk_add_f32 v[18:19], v[18:19], v[174:175]
	v_pk_fma_f32 v[176:177], v[20:21], v[20:21], v[176:177]
	v_pk_fma_f32 v[176:177], v[22:23], v[22:23], v[176:177]
	v_pk_fma_f32 v[176:177], v[16:17], v[16:17], v[176:177]
	v_pk_fma_f32 v[176:177], v[18:19], v[18:19], v[176:177]
	v_cvt_pk_bf16_f32 v20, v20, v21
	v_cvt_pk_bf16_f32 v21, v22, v23
	v_cvt_pk_bf16_f32 v22, v16, v17
	v_cvt_pk_bf16_f32 v23, v18, v19
	v_add_f32_e32 v184, v176, v177
	global_store_dwordx4 v205, v[28:31], s[8:9]
	global_store_dwordx4 v205, v[20:23], s[8:9] offset:256
	v_add_u32_e32 v205, 0x8000, v205
	v_lshlrev_b32_e32 v168, 16, v104
	v_and_b32_e32 v169, 0xffff0000, v104
	v_lshlrev_b32_e32 v170, 16, v105
	v_and_b32_e32 v171, 0xffff0000, v105
	v_lshlrev_b32_e32 v172, 16, v106
	v_and_b32_e32 v173, 0xffff0000, v106
	v_lshlrev_b32_e32 v174, 16, v107
	v_and_b32_e32 v175, 0xffff0000, v107
	v_pk_add_f32 v[12:13], v[12:13], v[168:169]
	v_pk_add_f32 v[14:15], v[14:15], v[170:171]
	v_pk_add_f32 v[8:9], v[8:9], v[172:173]
	v_pk_add_f32 v[10:11], v[10:11], v[174:175]
	v_pk_mul_f32 v[176:177], v[12:13], v[12:13]
	v_pk_fma_f32 v[176:177], v[14:15], v[14:15], v[176:177]
	v_pk_fma_f32 v[176:177], v[8:9], v[8:9], v[176:177]
	v_pk_fma_f32 v[176:177], v[10:11], v[10:11], v[176:177]
	v_cvt_pk_bf16_f32 v12, v12, v13
	v_cvt_pk_bf16_f32 v13, v14, v15
	v_cvt_pk_bf16_f32 v14, v8, v9
	v_cvt_pk_bf16_f32 v15, v10, v11
	v_lshlrev_b32_e32 v168, 16, v108
	v_and_b32_e32 v169, 0xffff0000, v108
	v_lshlrev_b32_e32 v170, 16, v109
	v_and_b32_e32 v171, 0xffff0000, v109
	v_lshlrev_b32_e32 v172, 16, v110
	v_and_b32_e32 v173, 0xffff0000, v110
	v_lshlrev_b32_e32 v174, 16, v111
	v_and_b32_e32 v175, 0xffff0000, v111
	v_pk_add_f32 v[4:5], v[4:5], v[168:169]
	v_pk_add_f32 v[6:7], v[6:7], v[170:171]
	v_pk_add_f32 v[0:1], v[0:1], v[172:173]
	v_pk_add_f32 v[2:3], v[2:3], v[174:175]
	v_pk_fma_f32 v[176:177], v[4:5], v[4:5], v[176:177]
	v_pk_fma_f32 v[176:177], v[6:7], v[6:7], v[176:177]
	v_pk_fma_f32 v[176:177], v[0:1], v[0:1], v[176:177]
	v_pk_fma_f32 v[176:177], v[2:3], v[2:3], v[176:177]
	v_cvt_pk_bf16_f32 v4, v4, v5
	v_cvt_pk_bf16_f32 v5, v6, v7
	v_cvt_pk_bf16_f32 v6, v0, v1
	v_cvt_pk_bf16_f32 v7, v2, v3
	v_add_f32_e32 v185, v176, v177
	global_store_dwordx4 v205, v[12:15], s[8:9]
	global_store_dwordx4 v205, v[4:7], s[8:9] offset:256
	ds_bpermute_b32 v168, v194, v178
	ds_bpermute_b32 v169, v194, v179
	ds_bpermute_b32 v170, v194, v180
	ds_bpermute_b32 v171, v194, v181
	ds_bpermute_b32 v172, v194, v182
	ds_bpermute_b32 v173, v194, v183
	ds_bpermute_b32 v174, v194, v184
	ds_bpermute_b32 v175, v194, v185
	s_waitcnt lgkmcnt(0)
	v_add_f32_e32 v178, v178, v168
	v_add_f32_e32 v179, v179, v169
	v_add_f32_e32 v180, v180, v170
	v_add_f32_e32 v181, v181, v171
	v_add_f32_e32 v182, v182, v172
	v_add_f32_e32 v183, v183, v173
	v_add_f32_e32 v184, v184, v174
	v_add_f32_e32 v185, v185, v175
	ds_bpermute_b32 v168, v193, v178
	ds_bpermute_b32 v169, v193, v179
	ds_bpermute_b32 v170, v193, v180
	ds_bpermute_b32 v171, v193, v181
	ds_bpermute_b32 v172, v193, v182
	ds_bpermute_b32 v173, v193, v183
	ds_bpermute_b32 v174, v193, v184
	ds_bpermute_b32 v175, v193, v185
	s_waitcnt lgkmcnt(0)
	v_add_f32_e32 v178, v178, v168
	v_add_f32_e32 v179, v179, v169
	v_add_f32_e32 v180, v180, v170
	v_add_f32_e32 v181, v181, v171
	v_add_f32_e32 v182, v182, v172
	v_add_f32_e32 v183, v183, v173
	v_add_f32_e32 v184, v184, v174
	v_add_f32_e32 v185, v185, v175
	s_and_saveexec_b64 s[24:25], s[2:3]
	global_atomic_add_f32 v206, v178, s[16:17]
	global_atomic_add_f32 v206, v179, s[16:17] offset:64
	global_atomic_add_f32 v206, v180, s[16:17] offset:128
	global_atomic_add_f32 v206, v181, s[16:17] offset:192
	global_atomic_add_f32 v206, v182, s[16:17] offset:512
	global_atomic_add_f32 v206, v183, s[16:17] offset:576
	global_atomic_add_f32 v206, v184, s[16:17] offset:640
	global_atomic_add_f32 v206, v185, s[16:17] offset:704
	s_or_b64 exec, exec, s[24:25]
	s_and_b64 vcc, exec, s[4:5]
	s_mov_b64 s[4:5], -1
	s_cbranch_vccnz .LBB0_963
	s_andn2_b64 vcc, exec, s[14:15]
	s_cbranch_vccnz .LBB0_962
	s_barrier
	s_branch .LBB0_962
